# attnA hand-written unit + gates epilogue; both blocks padded so all later code keeps baseline addresses
# speedup vs baseline: 1.0068x; 1.0068x over previous
; __device__ __forceinline__ float fexp2(float x) { return __builtin_amdgcn_exp2f(x); }
; __device__ __forceinline__ float frcp(float x) { return __builtin_amdgcn_rcpf(x); }
; __device__ __forceinline__ u32x4 pack8(f32x4 a, f32x4 b) { u32x4 w; w.x = pk_bf16(a[0], a[1]); w.y = pk_bf16(a[2], a[3]); w.z = pk_bf16(b[0], b[1]); w.w = pk_bf16(b[2], b[3]); return w; }
; #define TILE_FOR(...) \
;     _Pragma("unroll") for (int ai = 0; ai < 2; ++ai) _Pragma("unroll") for (int m = 0; m < 4; ++m) { const int row = rowb + ai * 128 + m * 16; \
;     _Pragma("unroll") for (int bj = 0; bj < 2; ++bj) { const int col = colb + bj * 128; f32x4& v0 = acc[ai][bj][m][0]; f32x4& v1 = acc[ai][bj][m][1]; __VA_ARGS__ } }
; __device__ __forceinline__ float sigmoidf_(float x) { return frcp(1.0f + fexp2(-x * LOG2E)); }
;     __device__ __forceinline__ bool operator()(f32x4 (&acc)[2][2][4][2], const pg8::Unit& u, int wr, int wc, int fr, int fq) const {
;     ...
;         else if (kind <= 8) {
;             const int gofs = (kind - 6) * 1024;
;             TILE_FOR( const f32x4 b0 = *(const f32x4*)(bgate + gofs + col); const f32x4 b1 = *(const f32x4*)(bgate + gofs + col + 4); f32x4 g0, g1;
;                       _Pragma("unroll") for (int j = 0; j < 4; ++j) { g0[j] = sigmoidf_(v0[j] + b0[j]); g1[j] = sigmoidf_(v1[j] + b1[j]); }
;                       *(u32x4*)(G + (size_t)row * GATEW + gofs + col) = pack8(g0, g1); ) }
.LBB0_142:
	s_andn2_b64 vcc, exec, s[74:75]
	s_cbranch_vccnz .LBB0_144
	s_load_dwordx2 s[40:41], s[26:27], 0xf0
	s_lshl_b32 s6, s42, 10
	s_add_i32 s74, s6, 0xffffe800
	s_ashr_i32 s75, s74, 31
	s_lshl_b64 s[6:7], s[74:75], 2
	s_waitcnt lgkmcnt(0)
	s_add_u32 s6, s40, s6
	s_addc_u32 s7, s41, s7
	v_lshlrev_b32_e32 v151, 2, v175
	global_load_dwordx4 v[180:183], v151, s[6:7]
	global_load_dwordx4 v[184:187], v151, s[6:7] offset:16
	global_load_dwordx4 v[188:191], v151, s[6:7] offset:512
	global_load_dwordx4 v[192:195], v151, s[6:7] offset:528
	v_readlane_b32 s40, v252, 17
	v_readlane_b32 s41, v252, 18
	s_lshl_b64 s[74:75], s[74:75], 1
	v_lshlrev_b32_e32 v142, 1, v175
	v_mov_b64_e32 v[152:153], s[40:41]
	v_mad_i64_i32 v[220:221], s[40:41], v150, s94, v[152:153]
	v_lshl_add_u64 v[220:221], v[220:221], 0, s[74:75]
	v_lshl_add_u64 v[220:221], v[220:221], 0, v[142:143]
	v_add_u32_e32 v176, 0x10, v150
	v_mad_i64_i32 v[222:223], s[40:41], v176, s94, v[152:153]
	v_lshl_add_u64 v[222:223], v[222:223], 0, s[74:75]
	v_lshl_add_u64 v[222:223], v[222:223], 0, v[142:143]
	v_add_u32_e32 v176, 0x20, v150
	v_mad_i64_i32 v[224:225], s[40:41], v176, s94, v[152:153]
	v_lshl_add_u64 v[224:225], v[224:225], 0, s[74:75]
	v_lshl_add_u64 v[224:225], v[224:225], 0, v[142:143]
	v_add_u32_e32 v176, 0x30, v150
	v_mad_i64_i32 v[226:227], s[40:41], v176, s94, v[152:153]
	v_lshl_add_u64 v[226:227], v[226:227], 0, s[74:75]
	v_lshl_add_u64 v[226:227], v[226:227], 0, v[142:143]
	v_add_u32_e32 v176, 0x80, v150
	v_mad_i64_i32 v[228:229], s[40:41], v176, s94, v[152:153]
	v_lshl_add_u64 v[228:229], v[228:229], 0, s[74:75]
	v_lshl_add_u64 v[228:229], v[228:229], 0, v[142:143]
	v_add_u32_e32 v176, 0x90, v150
	v_mad_i64_i32 v[230:231], s[40:41], v176, s94, v[152:153]
	v_lshl_add_u64 v[230:231], v[230:231], 0, s[74:75]
	v_lshl_add_u64 v[230:231], v[230:231], 0, v[142:143]
	v_add_u32_e32 v176, 0xa0, v150
	v_mad_i64_i32 v[232:233], s[40:41], v176, s94, v[152:153]
	v_lshl_add_u64 v[232:233], v[232:233], 0, s[74:75]
	v_lshl_add_u64 v[232:233], v[232:233], 0, v[142:143]
	v_add_u32_e32 v176, 0xb0, v150
	v_mad_i64_i32 v[234:235], s[40:41], v176, s94, v[152:153]
	v_lshl_add_u64 v[234:235], v[234:235], 0, s[74:75]
	v_lshl_add_u64 v[234:235], v[234:235], 0, v[142:143]
	s_waitcnt vmcnt(0)
	v_add_f32_e32 v196, v126, v180
	v_add_f32_e32 v197, v127, v181
	v_add_f32_e32 v198, v128, v182
	v_add_f32_e32 v199, v129, v183
	v_add_f32_e32 v200, v122, v184
	v_add_f32_e32 v201, v123, v185
	v_add_f32_e32 v202, v124, v186
	v_add_f32_e32 v203, v125, v187
	v_mul_f32_e32 v196, 0xbfb8aa3b, v196
	v_mul_f32_e32 v197, 0xbfb8aa3b, v197
	v_mul_f32_e32 v198, 0xbfb8aa3b, v198
	v_mul_f32_e32 v199, 0xbfb8aa3b, v199
	v_mul_f32_e32 v200, 0xbfb8aa3b, v200
	v_mul_f32_e32 v201, 0xbfb8aa3b, v201
	v_mul_f32_e32 v202, 0xbfb8aa3b, v202
	v_mul_f32_e32 v203, 0xbfb8aa3b, v203
	v_exp_f32_e32 v196, v196
	v_exp_f32_e32 v197, v197
	v_exp_f32_e32 v198, v198
	v_exp_f32_e32 v199, v199
	v_exp_f32_e32 v200, v200
	v_exp_f32_e32 v201, v201
	v_exp_f32_e32 v202, v202
	v_exp_f32_e32 v203, v203
	v_add_f32_e32 v196, 1.0, v196
	v_add_f32_e32 v197, 1.0, v197
	v_add_f32_e32 v198, 1.0, v198
	v_add_f32_e32 v199, 1.0, v199
	v_add_f32_e32 v200, 1.0, v200
	v_add_f32_e32 v201, 1.0, v201
	v_add_f32_e32 v202, 1.0, v202
	v_add_f32_e32 v203, 1.0, v203
	v_rcp_f32_e32 v196, v196
	v_rcp_f32_e32 v197, v197
	v_rcp_f32_e32 v198, v198
	v_rcp_f32_e32 v199, v199
	v_rcp_f32_e32 v200, v200
	v_rcp_f32_e32 v201, v201
	v_rcp_f32_e32 v202, v202
	v_rcp_f32_e32 v203, v203
	v_cvt_pk_bf16_f32 v212, v196, v197
	v_cvt_pk_bf16_f32 v213, v198, v199
	v_cvt_pk_bf16_f32 v214, v200, v201
	v_cvt_pk_bf16_f32 v215, v202, v203
	global_store_dwordx4 v[220:221], v[212:215], off
	v_add_f32_e32 v204, v114, v188
	v_add_f32_e32 v205, v115, v189
	v_add_f32_e32 v206, v116, v190
	v_add_f32_e32 v207, v117, v191
	v_add_f32_e32 v208, v106, v192
	v_add_f32_e32 v209, v107, v193
	v_add_f32_e32 v210, v108, v194
	v_add_f32_e32 v211, v109, v195
	v_mul_f32_e32 v204, 0xbfb8aa3b, v204
	v_mul_f32_e32 v205, 0xbfb8aa3b, v205
	v_mul_f32_e32 v206, 0xbfb8aa3b, v206
	v_mul_f32_e32 v207, 0xbfb8aa3b, v207
	v_mul_f32_e32 v208, 0xbfb8aa3b, v208
	v_mul_f32_e32 v209, 0xbfb8aa3b, v209
	v_mul_f32_e32 v210, 0xbfb8aa3b, v210
	v_mul_f32_e32 v211, 0xbfb8aa3b, v211
	v_exp_f32_e32 v204, v204
	v_exp_f32_e32 v205, v205
	v_exp_f32_e32 v206, v206
	v_exp_f32_e32 v207, v207
	v_exp_f32_e32 v208, v208
	v_exp_f32_e32 v209, v209
	v_exp_f32_e32 v210, v210
	v_exp_f32_e32 v211, v211
	v_add_f32_e32 v204, 1.0, v204
	v_add_f32_e32 v205, 1.0, v205
	v_add_f32_e32 v206, 1.0, v206
	v_add_f32_e32 v207, 1.0, v207
	v_add_f32_e32 v208, 1.0, v208
	v_add_f32_e32 v209, 1.0, v209
	v_add_f32_e32 v210, 1.0, v210
	v_add_f32_e32 v211, 1.0, v211
	v_rcp_f32_e32 v204, v204
	v_rcp_f32_e32 v205, v205
	v_rcp_f32_e32 v206, v206
	v_rcp_f32_e32 v207, v207
	v_rcp_f32_e32 v208, v208
	v_rcp_f32_e32 v209, v209
	v_rcp_f32_e32 v210, v210
	v_rcp_f32_e32 v211, v211
	v_cvt_pk_bf16_f32 v216, v204, v205
	v_cvt_pk_bf16_f32 v217, v206, v207
	v_cvt_pk_bf16_f32 v218, v208, v209
	v_cvt_pk_bf16_f32 v219, v210, v211
	global_store_dwordx4 v[220:221], v[216:219], off offset:256
	v_add_f32_e32 v196, v118, v180
	v_add_f32_e32 v197, v119, v181
	v_add_f32_e32 v198, v120, v182
	v_add_f32_e32 v199, v121, v183
	v_add_f32_e32 v200, v110, v184
	v_add_f32_e32 v201, v111, v185
	v_add_f32_e32 v202, v112, v186
	v_add_f32_e32 v203, v113, v187
	v_mul_f32_e32 v196, 0xbfb8aa3b, v196
	v_mul_f32_e32 v197, 0xbfb8aa3b, v197
	v_mul_f32_e32 v198, 0xbfb8aa3b, v198
	v_mul_f32_e32 v199, 0xbfb8aa3b, v199
	v_mul_f32_e32 v200, 0xbfb8aa3b, v200
	v_mul_f32_e32 v201, 0xbfb8aa3b, v201
	v_mul_f32_e32 v202, 0xbfb8aa3b, v202
; __device__ __forceinline__ float sigmoidf_(float x) { return frcp(1.0f + fexp2(-x * LOG2E)); }
; __device__ __forceinline__ u32x4 pack8(f32x4 a, f32x4 b) { u32x4 w; w.x = pk_bf16(a[0], a[1]); w.y = pk_bf16(a[2], a[3]); w.z = pk_bf16(b[0], b[1]); w.w = pk_bf16(b[2], b[3]); return w; }
; #define TILE_FOR(...) \
;     _Pragma("unroll") for (int ai = 0; ai < 2; ++ai) _Pragma("unroll") for (int m = 0; m < 4; ++m) { const int row = rowb + ai * 128 + m * 16; \
;     _Pragma("unroll") for (int bj = 0; bj < 2; ++bj) { const int col = colb + bj * 128; f32x4& v0 = acc[ai][bj][m][0]; f32x4& v1 = acc[ai][bj][m][1]; __VA_ARGS__ } }
;     __device__ __forceinline__ bool operator()(f32x4 (&acc)[2][2][4][2], const pg8::Unit& u, int wr, int wc, int fr, int fq) const {
;     ...
;             TILE_FOR( const f32x4 b0 = *(const f32x4*)(bgate + gofs + col); const f32x4 b1 = *(const f32x4*)(bgate + gofs + col + 4); f32x4 g0, g1;
;                       _Pragma("unroll") for (int j = 0; j < 4; ++j) { g0[j] = sigmoidf_(v0[j] + b0[j]); g1[j] = sigmoidf_(v1[j] + b1[j]); }
;                       *(u32x4*)(G + (size_t)row * GATEW + gofs + col) = pack8(g0, g1); ) }
	v_mul_f32_e32 v203, 0xbfb8aa3b, v203
	v_exp_f32_e32 v196, v196
	v_exp_f32_e32 v197, v197
	v_exp_f32_e32 v198, v198
	v_exp_f32_e32 v199, v199
	v_exp_f32_e32 v200, v200
	v_exp_f32_e32 v201, v201
	v_exp_f32_e32 v202, v202
	v_exp_f32_e32 v203, v203
	v_add_f32_e32 v196, 1.0, v196
	v_add_f32_e32 v197, 1.0, v197
	v_add_f32_e32 v198, 1.0, v198
	v_add_f32_e32 v199, 1.0, v199
	v_add_f32_e32 v200, 1.0, v200
	v_add_f32_e32 v201, 1.0, v201
	v_add_f32_e32 v202, 1.0, v202
	v_add_f32_e32 v203, 1.0, v203
	v_rcp_f32_e32 v196, v196
	v_rcp_f32_e32 v197, v197
	v_rcp_f32_e32 v198, v198
	v_rcp_f32_e32 v199, v199
	v_rcp_f32_e32 v200, v200
	v_rcp_f32_e32 v201, v201
	v_rcp_f32_e32 v202, v202
	v_rcp_f32_e32 v203, v203
	v_cvt_pk_bf16_f32 v212, v196, v197
	v_cvt_pk_bf16_f32 v213, v198, v199
	v_cvt_pk_bf16_f32 v214, v200, v201
	v_cvt_pk_bf16_f32 v215, v202, v203
	global_store_dwordx4 v[222:223], v[212:215], off
	v_add_f32_e32 v204, v98, v188
	v_add_f32_e32 v205, v99, v189
	v_add_f32_e32 v206, v100, v190
	v_add_f32_e32 v207, v101, v191
	v_add_f32_e32 v208, v90, v192
	v_add_f32_e32 v209, v91, v193
	v_add_f32_e32 v210, v92, v194
	v_add_f32_e32 v211, v93, v195
	v_mul_f32_e32 v204, 0xbfb8aa3b, v204
	v_mul_f32_e32 v205, 0xbfb8aa3b, v205
	v_mul_f32_e32 v206, 0xbfb8aa3b, v206
	v_mul_f32_e32 v207, 0xbfb8aa3b, v207
	v_mul_f32_e32 v208, 0xbfb8aa3b, v208
	v_mul_f32_e32 v209, 0xbfb8aa3b, v209
	v_mul_f32_e32 v210, 0xbfb8aa3b, v210
	v_mul_f32_e32 v211, 0xbfb8aa3b, v211
	v_exp_f32_e32 v204, v204
	v_exp_f32_e32 v205, v205
	v_exp_f32_e32 v206, v206
	v_exp_f32_e32 v207, v207
	v_exp_f32_e32 v208, v208
	v_exp_f32_e32 v209, v209
	v_exp_f32_e32 v210, v210
	v_exp_f32_e32 v211, v211
	v_add_f32_e32 v204, 1.0, v204
	v_add_f32_e32 v205, 1.0, v205
	v_add_f32_e32 v206, 1.0, v206
	v_add_f32_e32 v207, 1.0, v207
	v_add_f32_e32 v208, 1.0, v208
	v_add_f32_e32 v209, 1.0, v209
	v_add_f32_e32 v210, 1.0, v210
	v_add_f32_e32 v211, 1.0, v211
	v_rcp_f32_e32 v204, v204
	v_rcp_f32_e32 v205, v205
	v_rcp_f32_e32 v206, v206
	v_rcp_f32_e32 v207, v207
	v_rcp_f32_e32 v208, v208
	v_rcp_f32_e32 v209, v209
	v_rcp_f32_e32 v210, v210
	v_rcp_f32_e32 v211, v211
	v_cvt_pk_bf16_f32 v216, v204, v205
	v_cvt_pk_bf16_f32 v217, v206, v207
	v_cvt_pk_bf16_f32 v218, v208, v209
	v_cvt_pk_bf16_f32 v219, v210, v211
	global_store_dwordx4 v[222:223], v[216:219], off offset:256
	v_add_f32_e32 v196, v102, v180
	v_add_f32_e32 v197, v103, v181
	v_add_f32_e32 v198, v104, v182
	v_add_f32_e32 v199, v105, v183
	v_add_f32_e32 v200, v94, v184
	v_add_f32_e32 v201, v95, v185
	v_add_f32_e32 v202, v96, v186
	v_add_f32_e32 v203, v97, v187
	v_mul_f32_e32 v196, 0xbfb8aa3b, v196
	v_mul_f32_e32 v197, 0xbfb8aa3b, v197
	v_mul_f32_e32 v198, 0xbfb8aa3b, v198
	v_mul_f32_e32 v199, 0xbfb8aa3b, v199
	v_mul_f32_e32 v200, 0xbfb8aa3b, v200
	v_mul_f32_e32 v201, 0xbfb8aa3b, v201
	v_mul_f32_e32 v202, 0xbfb8aa3b, v202
	v_mul_f32_e32 v203, 0xbfb8aa3b, v203
	v_exp_f32_e32 v196, v196
	v_exp_f32_e32 v197, v197
	v_exp_f32_e32 v198, v198
	v_exp_f32_e32 v199, v199
	v_exp_f32_e32 v200, v200
	v_exp_f32_e32 v201, v201
	v_exp_f32_e32 v202, v202
	v_exp_f32_e32 v203, v203
	v_add_f32_e32 v196, 1.0, v196
	v_add_f32_e32 v197, 1.0, v197
	v_add_f32_e32 v198, 1.0, v198
	v_add_f32_e32 v199, 1.0, v199
	v_add_f32_e32 v200, 1.0, v200
	v_add_f32_e32 v201, 1.0, v201
	v_add_f32_e32 v202, 1.0, v202
	v_add_f32_e32 v203, 1.0, v203
	v_rcp_f32_e32 v196, v196
	v_rcp_f32_e32 v197, v197
	v_rcp_f32_e32 v198, v198
	v_rcp_f32_e32 v199, v199
	v_rcp_f32_e32 v200, v200
	v_rcp_f32_e32 v201, v201
	v_rcp_f32_e32 v202, v202
	v_rcp_f32_e32 v203, v203
	v_cvt_pk_bf16_f32 v212, v196, v197
	v_cvt_pk_bf16_f32 v213, v198, v199
	v_cvt_pk_bf16_f32 v214, v200, v201
	v_cvt_pk_bf16_f32 v215, v202, v203
	global_store_dwordx4 v[224:225], v[212:215], off
	v_add_f32_e32 v204, v82, v188
	v_add_f32_e32 v205, v83, v189
	v_add_f32_e32 v206, v84, v190
	v_add_f32_e32 v207, v85, v191
	v_add_f32_e32 v208, v74, v192
	v_add_f32_e32 v209, v75, v193
	v_add_f32_e32 v210, v76, v194
	v_add_f32_e32 v211, v77, v195
	v_mul_f32_e32 v204, 0xbfb8aa3b, v204
	v_mul_f32_e32 v205, 0xbfb8aa3b, v205
	v_mul_f32_e32 v206, 0xbfb8aa3b, v206
	v_mul_f32_e32 v207, 0xbfb8aa3b, v207
	v_mul_f32_e32 v208, 0xbfb8aa3b, v208
	v_mul_f32_e32 v209, 0xbfb8aa3b, v209
	v_mul_f32_e32 v210, 0xbfb8aa3b, v210
	v_mul_f32_e32 v211, 0xbfb8aa3b, v211
	v_exp_f32_e32 v204, v204
	v_exp_f32_e32 v205, v205
	v_exp_f32_e32 v206, v206
	v_exp_f32_e32 v207, v207
	v_exp_f32_e32 v208, v208
	v_exp_f32_e32 v209, v209
	v_exp_f32_e32 v210, v210
	v_exp_f32_e32 v211, v211
	v_add_f32_e32 v204, 1.0, v204
	v_add_f32_e32 v205, 1.0, v205
	v_add_f32_e32 v206, 1.0, v206
	v_add_f32_e32 v207, 1.0, v207
	v_add_f32_e32 v208, 1.0, v208
	v_add_f32_e32 v209, 1.0, v209
	v_add_f32_e32 v210, 1.0, v210
	v_add_f32_e32 v211, 1.0, v211
	v_rcp_f32_e32 v204, v204
	v_rcp_f32_e32 v205, v205
	v_rcp_f32_e32 v206, v206
	v_rcp_f32_e32 v207, v207
	v_rcp_f32_e32 v208, v208
	v_rcp_f32_e32 v209, v209
	v_rcp_f32_e32 v210, v210
	v_rcp_f32_e32 v211, v211
	v_cvt_pk_bf16_f32 v216, v204, v205
	v_cvt_pk_bf16_f32 v217, v206, v207
	v_cvt_pk_bf16_f32 v218, v208, v209
	v_cvt_pk_bf16_f32 v219, v210, v211
	global_store_dwordx4 v[224:225], v[216:219], off offset:256
	v_add_f32_e32 v196, v86, v180
	v_add_f32_e32 v197, v87, v181
	v_add_f32_e32 v198, v88, v182
	v_add_f32_e32 v199, v89, v183
	v_add_f32_e32 v200, v78, v184
	v_add_f32_e32 v201, v79, v185
	v_add_f32_e32 v202, v80, v186
	v_add_f32_e32 v203, v81, v187
	v_mul_f32_e32 v196, 0xbfb8aa3b, v196
	v_mul_f32_e32 v197, 0xbfb8aa3b, v197
	v_mul_f32_e32 v198, 0xbfb8aa3b, v198
	v_mul_f32_e32 v199, 0xbfb8aa3b, v199
	v_mul_f32_e32 v200, 0xbfb8aa3b, v200
	v_mul_f32_e32 v201, 0xbfb8aa3b, v201
; __device__ __forceinline__ float sigmoidf_(float x) { return frcp(1.0f + fexp2(-x * LOG2E)); }
; __device__ __forceinline__ u32x4 pack8(f32x4 a, f32x4 b) { u32x4 w; w.x = pk_bf16(a[0], a[1]); w.y = pk_bf16(a[2], a[3]); w.z = pk_bf16(b[0], b[1]); w.w = pk_bf16(b[2], b[3]); return w; }
; #define TILE_FOR(...) \
;     _Pragma("unroll") for (int ai = 0; ai < 2; ++ai) _Pragma("unroll") for (int m = 0; m < 4; ++m) { const int row = rowb + ai * 128 + m * 16; \
;     _Pragma("unroll") for (int bj = 0; bj < 2; ++bj) { const int col = colb + bj * 128; f32x4& v0 = acc[ai][bj][m][0]; f32x4& v1 = acc[ai][bj][m][1]; __VA_ARGS__ } }
;     __device__ __forceinline__ bool operator()(f32x4 (&acc)[2][2][4][2], const pg8::Unit& u, int wr, int wc, int fr, int fq) const {
;     ...
;             TILE_FOR( const f32x4 b0 = *(const f32x4*)(bgate + gofs + col); const f32x4 b1 = *(const f32x4*)(bgate + gofs + col + 4); f32x4 g0, g1;
;                       _Pragma("unroll") for (int j = 0; j < 4; ++j) { g0[j] = sigmoidf_(v0[j] + b0[j]); g1[j] = sigmoidf_(v1[j] + b1[j]); }
;                       *(u32x4*)(G + (size_t)row * GATEW + gofs + col) = pack8(g0, g1); ) }
	v_mul_f32_e32 v202, 0xbfb8aa3b, v202
	v_mul_f32_e32 v203, 0xbfb8aa3b, v203
	v_exp_f32_e32 v196, v196
	v_exp_f32_e32 v197, v197
	v_exp_f32_e32 v198, v198
	v_exp_f32_e32 v199, v199
	v_exp_f32_e32 v200, v200
	v_exp_f32_e32 v201, v201
	v_exp_f32_e32 v202, v202
	v_exp_f32_e32 v203, v203
	v_add_f32_e32 v196, 1.0, v196
	v_add_f32_e32 v197, 1.0, v197
	v_add_f32_e32 v198, 1.0, v198
	v_add_f32_e32 v199, 1.0, v199
	v_add_f32_e32 v200, 1.0, v200
	v_add_f32_e32 v201, 1.0, v201
	v_add_f32_e32 v202, 1.0, v202
	v_add_f32_e32 v203, 1.0, v203
	v_rcp_f32_e32 v196, v196
	v_rcp_f32_e32 v197, v197
	v_rcp_f32_e32 v198, v198
	v_rcp_f32_e32 v199, v199
	v_rcp_f32_e32 v200, v200
	v_rcp_f32_e32 v201, v201
	v_rcp_f32_e32 v202, v202
	v_rcp_f32_e32 v203, v203
	v_cvt_pk_bf16_f32 v212, v196, v197
	v_cvt_pk_bf16_f32 v213, v198, v199
	v_cvt_pk_bf16_f32 v214, v200, v201
	v_cvt_pk_bf16_f32 v215, v202, v203
	global_store_dwordx4 v[226:227], v[212:215], off
	v_add_f32_e32 v204, v70, v188
	v_add_f32_e32 v205, v71, v189
	v_add_f32_e32 v206, v72, v190
	v_add_f32_e32 v207, v73, v191
	v_add_f32_e32 v208, v66, v192
	v_add_f32_e32 v209, v67, v193
	v_add_f32_e32 v210, v68, v194
	v_add_f32_e32 v211, v69, v195
	v_mul_f32_e32 v204, 0xbfb8aa3b, v204
	v_mul_f32_e32 v205, 0xbfb8aa3b, v205
	v_mul_f32_e32 v206, 0xbfb8aa3b, v206
	v_mul_f32_e32 v207, 0xbfb8aa3b, v207
	v_mul_f32_e32 v208, 0xbfb8aa3b, v208
	v_mul_f32_e32 v209, 0xbfb8aa3b, v209
	v_mul_f32_e32 v210, 0xbfb8aa3b, v210
	v_mul_f32_e32 v211, 0xbfb8aa3b, v211
	v_exp_f32_e32 v204, v204
	v_exp_f32_e32 v205, v205
	v_exp_f32_e32 v206, v206
	v_exp_f32_e32 v207, v207
	v_exp_f32_e32 v208, v208
	v_exp_f32_e32 v209, v209
	v_exp_f32_e32 v210, v210
	v_exp_f32_e32 v211, v211
	v_add_f32_e32 v204, 1.0, v204
	v_add_f32_e32 v205, 1.0, v205
	v_add_f32_e32 v206, 1.0, v206
	v_add_f32_e32 v207, 1.0, v207
	v_add_f32_e32 v208, 1.0, v208
	v_add_f32_e32 v209, 1.0, v209
	v_add_f32_e32 v210, 1.0, v210
	v_add_f32_e32 v211, 1.0, v211
	v_rcp_f32_e32 v204, v204
	v_rcp_f32_e32 v205, v205
	v_rcp_f32_e32 v206, v206
	v_rcp_f32_e32 v207, v207
	v_rcp_f32_e32 v208, v208
	v_rcp_f32_e32 v209, v209
	v_rcp_f32_e32 v210, v210
	v_rcp_f32_e32 v211, v211
	v_cvt_pk_bf16_f32 v216, v204, v205
	v_cvt_pk_bf16_f32 v217, v206, v207
	v_cvt_pk_bf16_f32 v218, v208, v209
	v_cvt_pk_bf16_f32 v219, v210, v211
	global_store_dwordx4 v[226:227], v[216:219], off offset:256
	v_add_f32_e32 v196, v62, v180
	v_add_f32_e32 v197, v63, v181
	v_add_f32_e32 v198, v64, v182
	v_add_f32_e32 v199, v65, v183
	v_add_f32_e32 v200, v58, v184
	v_add_f32_e32 v201, v59, v185
	v_add_f32_e32 v202, v60, v186
	v_add_f32_e32 v203, v61, v187
	v_mul_f32_e32 v196, 0xbfb8aa3b, v196
	v_mul_f32_e32 v197, 0xbfb8aa3b, v197
	v_mul_f32_e32 v198, 0xbfb8aa3b, v198
	v_mul_f32_e32 v199, 0xbfb8aa3b, v199
	v_mul_f32_e32 v200, 0xbfb8aa3b, v200
	v_mul_f32_e32 v201, 0xbfb8aa3b, v201
	v_mul_f32_e32 v202, 0xbfb8aa3b, v202
	v_mul_f32_e32 v203, 0xbfb8aa3b, v203
	v_exp_f32_e32 v196, v196
	v_exp_f32_e32 v197, v197
	v_exp_f32_e32 v198, v198
	v_exp_f32_e32 v199, v199
	v_exp_f32_e32 v200, v200
	v_exp_f32_e32 v201, v201
	v_exp_f32_e32 v202, v202
	v_exp_f32_e32 v203, v203
	v_add_f32_e32 v196, 1.0, v196
	v_add_f32_e32 v197, 1.0, v197
	v_add_f32_e32 v198, 1.0, v198
	v_add_f32_e32 v199, 1.0, v199
	v_add_f32_e32 v200, 1.0, v200
	v_add_f32_e32 v201, 1.0, v201
	v_add_f32_e32 v202, 1.0, v202
	v_add_f32_e32 v203, 1.0, v203
	v_rcp_f32_e32 v196, v196
	v_rcp_f32_e32 v197, v197
	v_rcp_f32_e32 v198, v198
	v_rcp_f32_e32 v199, v199
	v_rcp_f32_e32 v200, v200
	v_rcp_f32_e32 v201, v201
	v_rcp_f32_e32 v202, v202
	v_rcp_f32_e32 v203, v203
	v_cvt_pk_bf16_f32 v212, v196, v197
	v_cvt_pk_bf16_f32 v213, v198, v199
	v_cvt_pk_bf16_f32 v214, v200, v201
	v_cvt_pk_bf16_f32 v215, v202, v203
	global_store_dwordx4 v[228:229], v[212:215], off
	v_add_f32_e32 v204, v50, v188
	v_add_f32_e32 v205, v51, v189
	v_add_f32_e32 v206, v52, v190
	v_add_f32_e32 v207, v53, v191
	v_add_f32_e32 v208, v42, v192
	v_add_f32_e32 v209, v43, v193
	v_add_f32_e32 v210, v44, v194
	v_add_f32_e32 v211, v45, v195
	v_mul_f32_e32 v204, 0xbfb8aa3b, v204
	v_mul_f32_e32 v205, 0xbfb8aa3b, v205
	v_mul_f32_e32 v206, 0xbfb8aa3b, v206
	v_mul_f32_e32 v207, 0xbfb8aa3b, v207
	v_mul_f32_e32 v208, 0xbfb8aa3b, v208
	v_mul_f32_e32 v209, 0xbfb8aa3b, v209
	v_mul_f32_e32 v210, 0xbfb8aa3b, v210
	v_mul_f32_e32 v211, 0xbfb8aa3b, v211
	v_exp_f32_e32 v204, v204
	v_exp_f32_e32 v205, v205
	v_exp_f32_e32 v206, v206
	v_exp_f32_e32 v207, v207
	v_exp_f32_e32 v208, v208
	v_exp_f32_e32 v209, v209
	v_exp_f32_e32 v210, v210
	v_exp_f32_e32 v211, v211
	v_add_f32_e32 v204, 1.0, v204
	v_add_f32_e32 v205, 1.0, v205
	v_add_f32_e32 v206, 1.0, v206
	v_add_f32_e32 v207, 1.0, v207
	v_add_f32_e32 v208, 1.0, v208
	v_add_f32_e32 v209, 1.0, v209
	v_add_f32_e32 v210, 1.0, v210
	v_add_f32_e32 v211, 1.0, v211
	v_rcp_f32_e32 v204, v204
	v_rcp_f32_e32 v205, v205
	v_rcp_f32_e32 v206, v206
	v_rcp_f32_e32 v207, v207
	v_rcp_f32_e32 v208, v208
	v_rcp_f32_e32 v209, v209
	v_rcp_f32_e32 v210, v210
	v_rcp_f32_e32 v211, v211
	v_cvt_pk_bf16_f32 v216, v204, v205
	v_cvt_pk_bf16_f32 v217, v206, v207
	v_cvt_pk_bf16_f32 v218, v208, v209
	v_cvt_pk_bf16_f32 v219, v210, v211
	global_store_dwordx4 v[228:229], v[216:219], off offset:256
	v_add_f32_e32 v196, v54, v180
	v_add_f32_e32 v197, v55, v181
	v_add_f32_e32 v198, v56, v182
	v_add_f32_e32 v199, v57, v183
	v_add_f32_e32 v200, v46, v184
	v_add_f32_e32 v201, v47, v185
	v_add_f32_e32 v202, v48, v186
	v_add_f32_e32 v203, v49, v187
	v_mul_f32_e32 v196, 0xbfb8aa3b, v196
	v_mul_f32_e32 v197, 0xbfb8aa3b, v197
	v_mul_f32_e32 v198, 0xbfb8aa3b, v198
	v_mul_f32_e32 v199, 0xbfb8aa3b, v199
	v_mul_f32_e32 v200, 0xbfb8aa3b, v200
; __device__ __forceinline__ float sigmoidf_(float x) { return frcp(1.0f + fexp2(-x * LOG2E)); }
; __device__ __forceinline__ u32x4 pack8(f32x4 a, f32x4 b) { u32x4 w; w.x = pk_bf16(a[0], a[1]); w.y = pk_bf16(a[2], a[3]); w.z = pk_bf16(b[0], b[1]); w.w = pk_bf16(b[2], b[3]); return w; }
; #define TILE_FOR(...) \
;     _Pragma("unroll") for (int ai = 0; ai < 2; ++ai) _Pragma("unroll") for (int m = 0; m < 4; ++m) { const int row = rowb + ai * 128 + m * 16; \
;     _Pragma("unroll") for (int bj = 0; bj < 2; ++bj) { const int col = colb + bj * 128; f32x4& v0 = acc[ai][bj][m][0]; f32x4& v1 = acc[ai][bj][m][1]; __VA_ARGS__ } }
;     __device__ __forceinline__ bool operator()(f32x4 (&acc)[2][2][4][2], const pg8::Unit& u, int wr, int wc, int fr, int fq) const {
;     ...
;             TILE_FOR( const f32x4 b0 = *(const f32x4*)(bgate + gofs + col); const f32x4 b1 = *(const f32x4*)(bgate + gofs + col + 4); f32x4 g0, g1;
;                       _Pragma("unroll") for (int j = 0; j < 4; ++j) { g0[j] = sigmoidf_(v0[j] + b0[j]); g1[j] = sigmoidf_(v1[j] + b1[j]); }
;                       *(u32x4*)(G + (size_t)row * GATEW + gofs + col) = pack8(g0, g1); ) }
	v_mul_f32_e32 v201, 0xbfb8aa3b, v201
	v_mul_f32_e32 v202, 0xbfb8aa3b, v202
	v_mul_f32_e32 v203, 0xbfb8aa3b, v203
	v_exp_f32_e32 v196, v196
	v_exp_f32_e32 v197, v197
	v_exp_f32_e32 v198, v198
	v_exp_f32_e32 v199, v199
	v_exp_f32_e32 v200, v200
	v_exp_f32_e32 v201, v201
	v_exp_f32_e32 v202, v202
	v_exp_f32_e32 v203, v203
	v_add_f32_e32 v196, 1.0, v196
	v_add_f32_e32 v197, 1.0, v197
	v_add_f32_e32 v198, 1.0, v198
	v_add_f32_e32 v199, 1.0, v199
	v_add_f32_e32 v200, 1.0, v200
	v_add_f32_e32 v201, 1.0, v201
	v_add_f32_e32 v202, 1.0, v202
	v_add_f32_e32 v203, 1.0, v203
	v_rcp_f32_e32 v196, v196
	v_rcp_f32_e32 v197, v197
	v_rcp_f32_e32 v198, v198
	v_rcp_f32_e32 v199, v199
	v_rcp_f32_e32 v200, v200
	v_rcp_f32_e32 v201, v201
	v_rcp_f32_e32 v202, v202
	v_rcp_f32_e32 v203, v203
	v_cvt_pk_bf16_f32 v212, v196, v197
	v_cvt_pk_bf16_f32 v213, v198, v199
	v_cvt_pk_bf16_f32 v214, v200, v201
	v_cvt_pk_bf16_f32 v215, v202, v203
	global_store_dwordx4 v[230:231], v[212:215], off
	v_add_f32_e32 v204, v34, v188
	v_add_f32_e32 v205, v35, v189
	v_add_f32_e32 v206, v36, v190
	v_add_f32_e32 v207, v37, v191
	v_add_f32_e32 v208, v26, v192
	v_add_f32_e32 v209, v27, v193
	v_add_f32_e32 v210, v28, v194
	v_add_f32_e32 v211, v29, v195
	v_mul_f32_e32 v204, 0xbfb8aa3b, v204
	v_mul_f32_e32 v205, 0xbfb8aa3b, v205
	v_mul_f32_e32 v206, 0xbfb8aa3b, v206
	v_mul_f32_e32 v207, 0xbfb8aa3b, v207
	v_mul_f32_e32 v208, 0xbfb8aa3b, v208
	v_mul_f32_e32 v209, 0xbfb8aa3b, v209
	v_mul_f32_e32 v210, 0xbfb8aa3b, v210
	v_mul_f32_e32 v211, 0xbfb8aa3b, v211
	v_exp_f32_e32 v204, v204
	v_exp_f32_e32 v205, v205
	v_exp_f32_e32 v206, v206
	v_exp_f32_e32 v207, v207
	v_exp_f32_e32 v208, v208
	v_exp_f32_e32 v209, v209
	v_exp_f32_e32 v210, v210
	v_exp_f32_e32 v211, v211
	v_add_f32_e32 v204, 1.0, v204
	v_add_f32_e32 v205, 1.0, v205
	v_add_f32_e32 v206, 1.0, v206
	v_add_f32_e32 v207, 1.0, v207
	v_add_f32_e32 v208, 1.0, v208
	v_add_f32_e32 v209, 1.0, v209
	v_add_f32_e32 v210, 1.0, v210
	v_add_f32_e32 v211, 1.0, v211
	v_rcp_f32_e32 v204, v204
	v_rcp_f32_e32 v205, v205
	v_rcp_f32_e32 v206, v206
	v_rcp_f32_e32 v207, v207
	v_rcp_f32_e32 v208, v208
	v_rcp_f32_e32 v209, v209
	v_rcp_f32_e32 v210, v210
	v_rcp_f32_e32 v211, v211
	v_cvt_pk_bf16_f32 v216, v204, v205
	v_cvt_pk_bf16_f32 v217, v206, v207
	v_cvt_pk_bf16_f32 v218, v208, v209
	v_cvt_pk_bf16_f32 v219, v210, v211
	global_store_dwordx4 v[230:231], v[216:219], off offset:256
	v_add_f32_e32 v196, v38, v180
	v_add_f32_e32 v197, v39, v181
	v_add_f32_e32 v198, v40, v182
	v_add_f32_e32 v199, v41, v183
	v_add_f32_e32 v200, v30, v184
	v_add_f32_e32 v201, v31, v185
	v_add_f32_e32 v202, v32, v186
	v_add_f32_e32 v203, v33, v187
	v_mul_f32_e32 v196, 0xbfb8aa3b, v196
	v_mul_f32_e32 v197, 0xbfb8aa3b, v197
	v_mul_f32_e32 v198, 0xbfb8aa3b, v198
	v_mul_f32_e32 v199, 0xbfb8aa3b, v199
	v_mul_f32_e32 v200, 0xbfb8aa3b, v200
	v_mul_f32_e32 v201, 0xbfb8aa3b, v201
	v_mul_f32_e32 v202, 0xbfb8aa3b, v202
	v_mul_f32_e32 v203, 0xbfb8aa3b, v203
	v_exp_f32_e32 v196, v196
	v_exp_f32_e32 v197, v197
	v_exp_f32_e32 v198, v198
	v_exp_f32_e32 v199, v199
	v_exp_f32_e32 v200, v200
	v_exp_f32_e32 v201, v201
	v_exp_f32_e32 v202, v202
	v_exp_f32_e32 v203, v203
	v_add_f32_e32 v196, 1.0, v196
	v_add_f32_e32 v197, 1.0, v197
	v_add_f32_e32 v198, 1.0, v198
	v_add_f32_e32 v199, 1.0, v199
	v_add_f32_e32 v200, 1.0, v200
	v_add_f32_e32 v201, 1.0, v201
	v_add_f32_e32 v202, 1.0, v202
	v_add_f32_e32 v203, 1.0, v203
	v_rcp_f32_e32 v196, v196
	v_rcp_f32_e32 v197, v197
	v_rcp_f32_e32 v198, v198
	v_rcp_f32_e32 v199, v199
	v_rcp_f32_e32 v200, v200
	v_rcp_f32_e32 v201, v201
	v_rcp_f32_e32 v202, v202
	v_rcp_f32_e32 v203, v203
	v_cvt_pk_bf16_f32 v212, v196, v197
	v_cvt_pk_bf16_f32 v213, v198, v199
	v_cvt_pk_bf16_f32 v214, v200, v201
	v_cvt_pk_bf16_f32 v215, v202, v203
	global_store_dwordx4 v[232:233], v[212:215], off
	v_add_f32_e32 v204, v18, v188
	v_add_f32_e32 v205, v19, v189
	v_add_f32_e32 v206, v20, v190
	v_add_f32_e32 v207, v21, v191
	v_add_f32_e32 v208, v10, v192
	v_add_f32_e32 v209, v11, v193
	v_add_f32_e32 v210, v12, v194
	v_add_f32_e32 v211, v13, v195
	v_mul_f32_e32 v204, 0xbfb8aa3b, v204
	v_mul_f32_e32 v205, 0xbfb8aa3b, v205
	v_mul_f32_e32 v206, 0xbfb8aa3b, v206
	v_mul_f32_e32 v207, 0xbfb8aa3b, v207
	v_mul_f32_e32 v208, 0xbfb8aa3b, v208
	v_mul_f32_e32 v209, 0xbfb8aa3b, v209
	v_mul_f32_e32 v210, 0xbfb8aa3b, v210
	v_mul_f32_e32 v211, 0xbfb8aa3b, v211
	v_exp_f32_e32 v204, v204
	v_exp_f32_e32 v205, v205
	v_exp_f32_e32 v206, v206
	v_exp_f32_e32 v207, v207
	v_exp_f32_e32 v208, v208
	v_exp_f32_e32 v209, v209
; __device__ __forceinline__ float sigmoidf_(float x) { return frcp(1.0f + fexp2(-x * LOG2E)); }
; __device__ __forceinline__ u32x4 pack8(f32x4 a, f32x4 b) { u32x4 w; w.x = pk_bf16(a[0], a[1]); w.y = pk_bf16(a[2], a[3]); w.z = pk_bf16(b[0], b[1]); w.w = pk_bf16(b[2], b[3]); return w; }
; #define TILE_FOR(...) \
;     _Pragma("unroll") for (int ai = 0; ai < 2; ++ai) _Pragma("unroll") for (int m = 0; m < 4; ++m) { const int row = rowb + ai * 128 + m * 16; \
;     _Pragma("unroll") for (int bj = 0; bj < 2; ++bj) { const int col = colb + bj * 128; f32x4& v0 = acc[ai][bj][m][0]; f32x4& v1 = acc[ai][bj][m][1]; __VA_ARGS__ } }
;     __device__ __forceinline__ bool operator()(f32x4 (&acc)[2][2][4][2], const pg8::Unit& u, int wr, int wc, int fr, int fq) const {
;     ...
;             TILE_FOR( const f32x4 b0 = *(const f32x4*)(bgate + gofs + col); const f32x4 b1 = *(const f32x4*)(bgate + gofs + col + 4); f32x4 g0, g1;
;                       _Pragma("unroll") for (int j = 0; j < 4; ++j) { g0[j] = sigmoidf_(v0[j] + b0[j]); g1[j] = sigmoidf_(v1[j] + b1[j]); }
;                       *(u32x4*)(G + (size_t)row * GATEW + gofs + col) = pack8(g0, g1); ) }
	v_exp_f32_e32 v210, v210
	v_exp_f32_e32 v211, v211
	v_add_f32_e32 v204, 1.0, v204
	v_add_f32_e32 v205, 1.0, v205
	v_add_f32_e32 v206, 1.0, v206
	v_add_f32_e32 v207, 1.0, v207
	v_add_f32_e32 v208, 1.0, v208
	v_add_f32_e32 v209, 1.0, v209
	v_add_f32_e32 v210, 1.0, v210
	v_add_f32_e32 v211, 1.0, v211
	v_rcp_f32_e32 v204, v204
	v_rcp_f32_e32 v205, v205
	v_rcp_f32_e32 v206, v206
	v_rcp_f32_e32 v207, v207
	v_rcp_f32_e32 v208, v208
	v_rcp_f32_e32 v209, v209
	v_rcp_f32_e32 v210, v210
	v_rcp_f32_e32 v211, v211
	v_cvt_pk_bf16_f32 v216, v204, v205
	v_cvt_pk_bf16_f32 v217, v206, v207
	v_cvt_pk_bf16_f32 v218, v208, v209
	v_cvt_pk_bf16_f32 v219, v210, v211
	global_store_dwordx4 v[232:233], v[216:219], off offset:256
	v_add_f32_e32 v196, v22, v180
	v_add_f32_e32 v197, v23, v181
	v_add_f32_e32 v198, v24, v182
	v_add_f32_e32 v199, v25, v183
	v_add_f32_e32 v200, v14, v184
	v_add_f32_e32 v201, v15, v185
	v_add_f32_e32 v202, v16, v186
	v_add_f32_e32 v203, v17, v187
	v_mul_f32_e32 v196, 0xbfb8aa3b, v196
	v_mul_f32_e32 v197, 0xbfb8aa3b, v197
	v_mul_f32_e32 v198, 0xbfb8aa3b, v198
	v_mul_f32_e32 v199, 0xbfb8aa3b, v199
	v_mul_f32_e32 v200, 0xbfb8aa3b, v200
	v_mul_f32_e32 v201, 0xbfb8aa3b, v201
	v_mul_f32_e32 v202, 0xbfb8aa3b, v202
	v_mul_f32_e32 v203, 0xbfb8aa3b, v203
	v_exp_f32_e32 v196, v196
	v_exp_f32_e32 v197, v197
	v_exp_f32_e32 v198, v198
	v_exp_f32_e32 v199, v199
	v_exp_f32_e32 v200, v200
	v_exp_f32_e32 v201, v201
	v_exp_f32_e32 v202, v202
	v_exp_f32_e32 v203, v203
	v_add_f32_e32 v196, 1.0, v196
	v_add_f32_e32 v197, 1.0, v197
	v_add_f32_e32 v198, 1.0, v198
	v_add_f32_e32 v199, 1.0, v199
	v_add_f32_e32 v200, 1.0, v200
	v_add_f32_e32 v201, 1.0, v201
	v_add_f32_e32 v202, 1.0, v202
	v_add_f32_e32 v203, 1.0, v203
	v_rcp_f32_e32 v196, v196
	v_rcp_f32_e32 v197, v197
	v_rcp_f32_e32 v198, v198
	v_rcp_f32_e32 v199, v199
	v_rcp_f32_e32 v200, v200
	v_rcp_f32_e32 v201, v201
	v_rcp_f32_e32 v202, v202
	v_rcp_f32_e32 v203, v203
	v_cvt_pk_bf16_f32 v212, v196, v197
	v_cvt_pk_bf16_f32 v213, v198, v199
	v_cvt_pk_bf16_f32 v214, v200, v201
	v_cvt_pk_bf16_f32 v215, v202, v203
	global_store_dwordx4 v[234:235], v[212:215], off
	v_add_f32_e32 v204, v6, v188
	v_add_f32_e32 v205, v7, v189
	v_add_f32_e32 v206, v8, v190
	v_add_f32_e32 v207, v9, v191
	v_add_f32_e32 v208, v2, v192
	v_add_f32_e32 v209, v3, v193
	v_add_f32_e32 v210, v4, v194
	v_add_f32_e32 v211, v5, v195
	v_mul_f32_e32 v204, 0xbfb8aa3b, v204
	v_mul_f32_e32 v205, 0xbfb8aa3b, v205
	v_mul_f32_e32 v206, 0xbfb8aa3b, v206
	v_mul_f32_e32 v207, 0xbfb8aa3b, v207
	v_mul_f32_e32 v208, 0xbfb8aa3b, v208
	v_mul_f32_e32 v209, 0xbfb8aa3b, v209
	v_mul_f32_e32 v210, 0xbfb8aa3b, v210
	v_mul_f32_e32 v211, 0xbfb8aa3b, v211
	v_exp_f32_e32 v204, v204
	v_exp_f32_e32 v205, v205
	v_exp_f32_e32 v206, v206
	v_exp_f32_e32 v207, v207
	v_exp_f32_e32 v208, v208
	v_exp_f32_e32 v209, v209
	v_exp_f32_e32 v210, v210
	v_exp_f32_e32 v211, v211
	v_add_f32_e32 v204, 1.0, v204
	v_add_f32_e32 v205, 1.0, v205
	v_add_f32_e32 v206, 1.0, v206
	v_add_f32_e32 v207, 1.0, v207
	v_add_f32_e32 v208, 1.0, v208
	v_add_f32_e32 v209, 1.0, v209
	v_add_f32_e32 v210, 1.0, v210
	v_add_f32_e32 v211, 1.0, v211
	v_rcp_f32_e32 v204, v204
	v_rcp_f32_e32 v205, v205
	v_rcp_f32_e32 v206, v206
	v_rcp_f32_e32 v207, v207
	v_rcp_f32_e32 v208, v208
	v_rcp_f32_e32 v209, v209
	v_rcp_f32_e32 v210, v210
	v_rcp_f32_e32 v211, v211
	v_cvt_pk_bf16_f32 v216, v204, v205
	v_cvt_pk_bf16_f32 v217, v206, v207
	v_cvt_pk_bf16_f32 v218, v208, v209
	v_cvt_pk_bf16_f32 v219, v210, v211
	global_store_dwordx4 v[234:235], v[216:219], off offset:256
	s_branch .Lgates_end
	s_nop 0
	s_nop 0
	s_nop 0
	s_nop 0
	s_nop 0
	s_nop 0
	s_nop 0
	s_nop 0
	s_nop 0
	s_nop 0
	s_nop 0
	s_nop 0
	s_nop 0
	s_nop 0
	s_nop 0
	s_nop 0
	s_nop 0
	s_nop 0
	s_nop 0
	s_nop 0
	s_nop 0
	s_nop 0
	s_nop 0
	s_nop 0
	s_nop 0
	s_nop 0
	s_nop 0
	s_nop 0
	s_nop 0
	s_nop 0
	s_nop 0
	s_nop 0
	s_nop 0
	s_nop 0
	s_nop 0
	s_nop 0
	s_nop 0
	s_nop 0
	s_nop 0
	s_nop 0
	s_nop 0
	s_nop 0
	s_nop 0
	s_nop 0
	s_nop 0
	s_nop 0
	s_nop 0
	s_nop 0
	s_nop 0
	s_nop 0
	s_nop 0
	s_nop 0
	s_nop 0
	s_nop 0
	s_nop 0
	s_nop 0
	s_nop 0
	s_nop 0
	s_nop 0
	s_nop 0
	s_nop 0
	s_nop 0
	s_nop 0
	s_nop 0
	s_nop 0
	s_nop 0
	s_nop 0
	s_nop 0
	s_nop 0
	s_nop 0
	s_nop 0
	s_nop 0
	s_nop 0
	s_nop 0
	s_nop 0
	s_nop 0
	s_nop 0
	s_nop 0
	s_nop 0
	s_nop 0
	s_nop 0
	s_nop 0
	s_nop 0
	s_nop 0
	s_nop 0
	s_nop 0
	s_nop 0
	s_nop 0
	s_nop 0
	s_nop 0
	s_nop 0
	s_nop 0
	s_nop 0
	s_nop 0
	s_nop 0
	s_nop 0
	s_nop 0
	s_nop 0
	s_nop 0
	s_nop 0
.Lgates_end:
.LBB0_144:
	s_cbranch_execnz .LBB0_178
	s_branch .LBB0_149

; #define A_WAITBAR(ahead) do { if ((ahead) >= 2) asm volatile("s_waitcnt vmcnt(8)" ::: "memory"); else if ((ahead) == 1) asm volatile("s_waitcnt vmcnt(4)" ::: "memory"); else asm volatile("s_waitcnt vmcnt(0)" ::: "memory"); \
;         __builtin_amdgcn_s_barrier(); asm volatile("" ::: "memory"); } while (0)
; __device__ __forceinline__ void attnA_unit(const P2Ctx& C, int b, int h, int qb) {
;     ...
;     const int kkey = 8 * wid + (lane >> 3), kchs = (lane & 7) ^ ((kkey >> 1) & 7);
;     const bf16_t* ksrc = C.Kb + ((size_t)trow0 + kkey) * DM + h * 128 + kchs * 8;
;     const bf16_t* vsrc[2];
; #pragma unroll
;     for (int i = 0; i < 2; ++i) { const int p = 2 * wid + i, kg = p >> 1, cbv = 2 * (p & 1) + (lane >> 5), vkey = kg * 8 + ((lane >> 2) & 7), vch = cbv * 4 + (lane & 3);
;         vsrc[i] = C.Vb + ((size_t)trow0 + vkey) * DM + h * 128 + vch * 8; }
;     ...
;     f32x16 o[4];
; #pragma unroll
;     for (int cb = 0; cb < 4; ++cb)
; #pragma unroll
;         for (int r = 0; r < 16; ++r) o[cb][r] = 0.f;
;     float mhat = 0.f, l = 0.f;
;     bf16x8 pf_[4];
; #pragma unroll
;     for (int i = 0; i < 4; ++i) pf_[i] = (bf16x8){0, 0, 0, 0, 0, 0, 0, 0};
;     ...
;     A_DMA(0); A_DMA(1);
;     A_WAITBAR(1);
;     { if (2 < NT && !(pf & 16)) A_DMA(2);
.LBB0_572:
	s_andn2_b64 vcc, exec, s[6:7]
	s_cbranch_vccnz .LBB0_614
	s_sub_i32 s6, s37, 32
	s_and_b32 s11, s6, 7
	s_lshr_b32 s6, s6, 3
	s_sub_i32 s10, 15, s6
	s_lshr_b32 s8, s83, 2
	s_and_b32 s9, s83, 3
	s_lshl_b32 s12, s10, 1
	s_add_i32 s12, s12, 2
	s_lshr_b32 s6, s9, 1
	s_lshl_b32 s13, s10, 1
	s_add_i32 s13, s13, s6
	s_add_i32 s13, s13, 1
	s_lshl_b32 s22, s83, 10
	s_lshl_b32 s23, s83, 11
	s_add_i32 s23, s23, 0x4000
	s_lshl_b32 s6, s10, 7
	s_lshl_b32 s7, s9, 5
	s_add_i32 s15, s6, s7
	s_add_i32 s26, s15, 0xffffff01
	s_mov_b32 s25, 0
	v_and_b32_e32 v100, 31, v219
	v_lshrrev_b32_e32 v101, 5, v219
	s_lshl_b32 s6, s11, 11
	s_add_i32 s6, s6, s15
	s_lshl_b32 s6, s6, 11
	s_lshl_b32 s7, s81, 1
	s_add_i32 s6, s6, s7
	s_lshl_b32 s7, s8, 7
	s_add_i32 s6, s6, s7
	s_add_u32 s20, s76, s6
	s_addc_u32 s21, s77, 0
	v_lshlrev_b32_e32 v102, 11, v100
	v_lshl_add_u32 v102, v101, 4, v102
	global_load_dwordx4 v[164:167], v102, s[20:21]
	global_load_dwordx4 v[168:171], v102, s[20:21] offset:32
	global_load_dwordx4 v[172:175], v102, s[20:21] offset:64
	global_load_dwordx4 v[176:179], v102, s[20:21] offset:96
	s_lshl_b32 s6, s11, 22
	s_lshl_b32 s7, s81, 1
	s_add_i32 s6, s6, s7
	s_add_u32 s16, s72, s6
	s_addc_u32 s17, s73, 0
	s_add_u32 s18, s74, s6
	s_addc_u32 s19, s75, 0
	s_mov_b32 s24, 0
	v_lshrrev_b32_e32 v103, 3, v219
	s_lshl_b32 s6, s83, 3
	v_add_u32_e32 v103, s6, v103
	v_bfe_u32 v104, v103, 1, 3
	v_and_b32_e32 v105, 7, v219
	v_xor_b32_e32 v104, v104, v105
	v_lshlrev_b32_e32 v104, 4, v104
	v_lshl_add_u32 v197, v103, 11, v104
	v_bfe_u32 v103, v219, 2, 3
	v_add_u32_e32 v103, s6, v103
	v_and_b32_e32 v104, 3, v219
	v_lshlrev_b32_e32 v104, 4, v104
	v_lshl_add_u32 v104, v101, 6, v104
	v_lshl_add_u32 v198, v103, 11, v104
	s_and_b32 s6, s24, 3
	s_lshl_b32 s6, s6, 15
	s_add_i32 s7, s6, s22
	s_mov_b32 m0, s7
	s_add_u32 s20, s16, 0x80
	s_addc_u32 s21, s17, 0
	s_add_i32 s29, s6, s23
	global_load_lds_dwordx4 v197, s[16:17]
	s_add_i32 m0, s7, 0x2000
	s_add_u32 s16, s16, 0x20000
	s_addc_u32 s17, s17, 0
	s_nop 0
	global_load_lds_dwordx4 v197, s[20:21]
	s_mov_b32 m0, s29
	s_add_u32 s20, s18, 0x80
	s_addc_u32 s21, s19, 0
	s_nop 0
	global_load_lds_dwordx4 v198, s[18:19]
	s_add_i32 m0, s29, 0x400
	s_add_u32 s18, s18, 0x20000
	s_addc_u32 s19, s19, 0
	s_add_i32 s24, s24, 1
	global_load_lds_dwordx4 v198, s[20:21]
	s_and_b32 s6, s24, 3
	s_lshl_b32 s6, s6, 15
	s_add_i32 s7, s6, s22
	s_mov_b32 m0, s7
	s_add_u32 s20, s16, 0x80
	s_addc_u32 s21, s17, 0
	s_add_i32 s29, s6, s23
	global_load_lds_dwordx4 v197, s[16:17]
	s_add_i32 m0, s7, 0x2000
	s_add_u32 s16, s16, 0x20000
	s_addc_u32 s17, s17, 0
	s_nop 0
	global_load_lds_dwordx4 v197, s[20:21]
	s_mov_b32 m0, s29
	s_add_u32 s20, s18, 0x80
	s_addc_u32 s21, s19, 0
	s_nop 0
	global_load_lds_dwordx4 v198, s[18:19]
	s_add_i32 m0, s29, 0x400
	s_add_u32 s18, s18, 0x20000
	s_addc_u32 s19, s19, 0
	s_add_i32 s24, s24, 1
	global_load_lds_dwordx4 v198, s[20:21]
	v_bfe_u32 v103, v100, 1, 3
	v_lshlrev_b32_e32 v104, 7, v100
	s_lshl_b32 s6, s8, 13
	v_add_u32_e32 v104, s6, v104
	v_or_b32_e32 v105, 0, v101
	v_xor_b32_e32 v105, v105, v103
	v_lshl_add_u32 v200, v105, 4, v104
	v_or_b32_e32 v105, 2, v101
	v_xor_b32_e32 v105, v105, v103
	v_lshl_add_u32 v201, v105, 4, v104
	v_or_b32_e32 v105, 4, v101
	v_xor_b32_e32 v105, v105, v103
	v_lshl_add_u32 v202, v105, 4, v104
	v_or_b32_e32 v105, 6, v101
	v_xor_b32_e32 v105, v105, v103
	v_lshl_add_u32 v203, v105, 4, v104
	v_bfe_u32 v103, v219, 2, 2
	v_lshl_add_u32 v103, v101, 2, v103
	v_lshlrev_b32_e32 v103, 6, v103
	v_bfe_u32 v104, v219, 4, 1
	v_lshl_add_u32 v103, v104, 5, v103
	v_and_b32_e32 v104, 3, v219
	v_lshl_add_u32 v103, v104, 3, v103
	v_add_u32_e32 v204, 0x4000, v103
	s_sub_i32 s6, 0x120, s15
	s_lshl_b32 s6, s6, 2
	s_add_i32 s6, s6, 0x22400
	v_lshlrev_b32_e32 v103, 4, v101
	v_lshlrev_b32_e32 v104, 2, v100
	v_sub_u32_e32 v103, v103, v104
	v_add_u32_e32 v236, s6, v103
	v_cmp_gt_u32_e32 vcc, 0x160, v196
	s_and_saveexec_b64 s[6:7], vcc
	s_cbranch_execz .LaA_padskip_1
	v_subrev_u32_e32 v103, 0x60, v196
	v_max_i32_e32 v104, 0, v103
	v_lshl_add_u32 v104, v104, 2, s42
	ds_read_b32 v105, v104
	v_cmp_gt_i32_e32 vcc, 0, v103
	v_mov_b32_e32 v106, 0x22400
	v_lshl_add_u32 v104, v196, 2, v106
	s_waitcnt lgkmcnt(0)
	v_cndmask_b32_e64 v105, v105, 0, vcc
	ds_write_b32 v104, v105
.LaA_padskip_1:
	s_or_b64 exec, exec, s[6:7]
	v_mov_b32_e32 v4, 0
	v_mov_b32_e32 v5, 0
	v_mov_b32_e32 v6, 0
	v_mov_b32_e32 v7, 0
	v_mov_b32_e32 v8, 0
	v_mov_b32_e32 v9, 0
	v_mov_b32_e32 v10, 0
	v_mov_b32_e32 v11, 0
	v_mov_b32_e32 v12, 0
	v_mov_b32_e32 v13, 0
	v_mov_b32_e32 v14, 0
	v_mov_b32_e32 v15, 0
	v_mov_b32_e32 v16, 0
	v_mov_b32_e32 v17, 0
	v_mov_b32_e32 v18, 0
	v_mov_b32_e32 v19, 0
	v_mov_b32_e32 v20, 0
	v_mov_b32_e32 v21, 0
	v_mov_b32_e32 v22, 0
	v_mov_b32_e32 v23, 0
	v_mov_b32_e32 v24, 0
	v_mov_b32_e32 v25, 0
	v_mov_b32_e32 v26, 0
	v_mov_b32_e32 v27, 0
	v_mov_b32_e32 v28, 0
	v_mov_b32_e32 v29, 0
	v_mov_b32_e32 v30, 0
	v_mov_b32_e32 v31, 0
	v_mov_b32_e32 v32, 0
	v_mov_b32_e32 v33, 0
	v_mov_b32_e32 v34, 0
	v_mov_b32_e32 v35, 0
	v_mov_b32_e32 v36, 0
	v_mov_b32_e32 v37, 0
	v_mov_b32_e32 v38, 0
	v_mov_b32_e32 v39, 0
	v_mov_b32_e32 v40, 0
	v_mov_b32_e32 v41, 0
	v_mov_b32_e32 v42, 0
	v_mov_b32_e32 v43, 0
	v_mov_b32_e32 v44, 0
	v_mov_b32_e32 v45, 0
	v_mov_b32_e32 v46, 0
	v_mov_b32_e32 v47, 0
	v_mov_b32_e32 v48, 0
	v_mov_b32_e32 v49, 0
	v_mov_b32_e32 v50, 0
	v_mov_b32_e32 v51, 0
	v_mov_b32_e32 v52, 0
	v_mov_b32_e32 v53, 0
	v_mov_b32_e32 v54, 0
	v_mov_b32_e32 v55, 0
	v_mov_b32_e32 v56, 0
	v_mov_b32_e32 v57, 0
	v_mov_b32_e32 v58, 0
	v_mov_b32_e32 v59, 0
	v_mov_b32_e32 v60, 0
	v_mov_b32_e32 v61, 0
	v_mov_b32_e32 v62, 0
	v_mov_b32_e32 v63, 0
	v_mov_b32_e32 v64, 0
	v_mov_b32_e32 v65, 0
	v_mov_b32_e32 v66, 0
	v_mov_b32_e32 v67, 0
	v_mov_b32_e32 v220, 0
	v_mov_b32_e32 v221, 0
	v_mov_b32_e32 v222, 0
	v_mov_b32_e32 v223, 0
	v_mov_b32_e32 v224, 0
	v_mov_b32_e32 v225, 0
	v_mov_b32_e32 v226, 0
	v_mov_b32_e32 v227, 0
	v_mov_b32_e32 v228, 0
	v_mov_b32_e32 v229, 0
	v_mov_b32_e32 v230, 0
	v_mov_b32_e32 v231, 0
	v_mov_b32_e32 v232, 0
	v_mov_b32_e32 v233, 0
	v_mov_b32_e32 v234, 0
	v_mov_b32_e32 v235, 0
	v_mov_b32_e32 v240, 0
	v_mov_b32_e32 v241, 0
	s_mov_b32 s14, 0
	s_waitcnt vmcnt(4) lgkmcnt(0)
	s_barrier
	s_cmp_lt_u32 s24, s12
	s_cbranch_scc0 .LaA_nodma_2
	s_and_b32 s6, s24, 3
	s_lshl_b32 s6, s6, 15
	s_add_i32 s7, s6, s22
	s_mov_b32 m0, s7
	s_add_u32 s20, s16, 0x80
	s_addc_u32 s21, s17, 0
	s_add_i32 s29, s6, s23
	global_load_lds_dwordx4 v197, s[16:17]
	s_add_i32 m0, s7, 0x2000
	s_add_u32 s16, s16, 0x20000
	s_addc_u32 s17, s17, 0
	s_nop 0
	global_load_lds_dwordx4 v197, s[20:21]
	s_mov_b32 m0, s29
	s_add_u32 s20, s18, 0x80
	s_addc_u32 s21, s19, 0
	s_nop 0
	global_load_lds_dwordx4 v198, s[18:19]
	s_add_i32 m0, s29, 0x400
	s_add_u32 s18, s18, 0x20000
	s_addc_u32 s19, s19, 0
	s_add_i32 s24, s24, 1
	global_load_lds_dwordx4 v198, s[20:21]

; __device__ __forceinline__ void attnA_unit(const P2Ctx& C, int b, int h, int qb) {
;     ...
;     for (int kt = 1; kt < NT; ++kt) {
;         if (kt + 2 < NT && !(pf & 16)) A_DMA(kt + 2);
.LaA_loop:
	s_cmp_lt_u32 s24, s12
	s_cbranch_scc0 .LaA_nodma_7
	s_and_b32 s6, s24, 3
	s_lshl_b32 s6, s6, 15
	s_add_i32 s7, s6, s22
	s_mov_b32 m0, s7
	s_add_u32 s20, s16, 0x80
	s_addc_u32 s21, s17, 0
	s_add_i32 s29, s6, s23
	global_load_lds_dwordx4 v197, s[16:17]
	s_add_i32 m0, s7, 0x2000
	s_add_u32 s16, s16, 0x20000
	s_addc_u32 s17, s17, 0
	s_nop 0
	global_load_lds_dwordx4 v197, s[20:21]
	s_mov_b32 m0, s29
	s_add_u32 s20, s18, 0x80
	s_addc_u32 s21, s19, 0
	s_nop 0
	global_load_lds_dwordx4 v198, s[18:19]
	s_add_i32 m0, s29, 0x400
	s_add_u32 s18, s18, 0x20000
	s_addc_u32 s19, s19, 0
	s_add_i32 s24, s24, 1
	global_load_lds_dwordx4 v198, s[20:21]

; #define LAS __attribute__((address_space(3)))
; __device__ __forceinline__ void attnA_unit(const P2Ctx& C, int b, int h, int qb) {
;     ...
;     if (NT - 1 < ntw && !(pf & 2)) A_PV(NT - 1);
;     __syncthreads();
;     ...
;     l += __shfl_xor(l, 32);
;     const float inv = 1.0f / l;
;     LAS float* X2 = (LAS float*)(lds + 65536);
;     if (comp == 1) {
; #pragma unroll
;         for (int cb = 0; cb < 4; ++cb)
; #pragma unroll
;             for (int r = 0; r < 16; ++r) X2[((qs * 4 + cb) * 16 + r) * 64 + lane] = o[cb][r] * inv;
;     }
;     __syncthreads();
.LaA_nofinalpv_13:
	s_waitcnt lgkmcnt(0)
	s_barrier
	v_mov_b32_e32 v243, v241
	s_nop 1
	v_permlane32_swap_b32 v243, v241
	v_add_f32_e32 v241, v243, v241
	v_rcp_f32_e32 v241, v241
	s_lshl_b32 s6, s9, 14
	s_add_i32 s6, s6, 0x10000
	v_lshlrev_b32_e32 v2, 2, v219
	v_add_u32_e32 v2, s6, v2
	s_cmp_eq_u32 s8, 0
	s_cbranch_scc1 .LaA_comp0_14
	s_nop 7
	s_nop 3
	v_mul_f32_e32 v68, v4, v241
	ds_write_b32 v2, v68 offset:0
	v_mul_f32_e32 v69, v5, v241
	ds_write_b32 v2, v69 offset:256
	v_mul_f32_e32 v68, v6, v241
	ds_write_b32 v2, v68 offset:512
	v_mul_f32_e32 v69, v7, v241
	ds_write_b32 v2, v69 offset:768
	v_mul_f32_e32 v68, v8, v241
	ds_write_b32 v2, v68 offset:1024
	v_mul_f32_e32 v69, v9, v241
	ds_write_b32 v2, v69 offset:1280
	v_mul_f32_e32 v68, v10, v241
	ds_write_b32 v2, v68 offset:1536
	v_mul_f32_e32 v69, v11, v241
	ds_write_b32 v2, v69 offset:1792
	v_mul_f32_e32 v68, v12, v241
	ds_write_b32 v2, v68 offset:2048
	v_mul_f32_e32 v69, v13, v241
	ds_write_b32 v2, v69 offset:2304
	v_mul_f32_e32 v68, v14, v241
	ds_write_b32 v2, v68 offset:2560
	v_mul_f32_e32 v69, v15, v241
	ds_write_b32 v2, v69 offset:2816
	v_mul_f32_e32 v68, v16, v241
	ds_write_b32 v2, v68 offset:3072
	v_mul_f32_e32 v69, v17, v241
	ds_write_b32 v2, v69 offset:3328
	v_mul_f32_e32 v68, v18, v241
	ds_write_b32 v2, v68 offset:3584
	v_mul_f32_e32 v69, v19, v241
	ds_write_b32 v2, v69 offset:3840
	v_mul_f32_e32 v68, v20, v241
	ds_write_b32 v2, v68 offset:4096
	v_mul_f32_e32 v69, v21, v241
	ds_write_b32 v2, v69 offset:4352
	v_mul_f32_e32 v68, v22, v241
	ds_write_b32 v2, v68 offset:4608
	v_mul_f32_e32 v69, v23, v241
	ds_write_b32 v2, v69 offset:4864
	v_mul_f32_e32 v68, v24, v241
	ds_write_b32 v2, v68 offset:5120
	v_mul_f32_e32 v69, v25, v241
	ds_write_b32 v2, v69 offset:5376
	v_mul_f32_e32 v68, v26, v241
	ds_write_b32 v2, v68 offset:5632
	v_mul_f32_e32 v69, v27, v241
	ds_write_b32 v2, v69 offset:5888
	v_mul_f32_e32 v68, v28, v241
	ds_write_b32 v2, v68 offset:6144
	v_mul_f32_e32 v69, v29, v241
	ds_write_b32 v2, v69 offset:6400
	v_mul_f32_e32 v68, v30, v241
	ds_write_b32 v2, v68 offset:6656
	v_mul_f32_e32 v69, v31, v241
	ds_write_b32 v2, v69 offset:6912
	v_mul_f32_e32 v68, v32, v241
	ds_write_b32 v2, v68 offset:7168
	v_mul_f32_e32 v69, v33, v241
	ds_write_b32 v2, v69 offset:7424
	v_mul_f32_e32 v68, v34, v241
	ds_write_b32 v2, v68 offset:7680
	v_mul_f32_e32 v69, v35, v241
	ds_write_b32 v2, v69 offset:7936
	v_mul_f32_e32 v68, v36, v241
	ds_write_b32 v2, v68 offset:8192
	v_mul_f32_e32 v69, v37, v241
	ds_write_b32 v2, v69 offset:8448
	v_mul_f32_e32 v68, v38, v241
	ds_write_b32 v2, v68 offset:8704
	v_mul_f32_e32 v69, v39, v241
	ds_write_b32 v2, v69 offset:8960
	v_mul_f32_e32 v68, v40, v241
	ds_write_b32 v2, v68 offset:9216
	v_mul_f32_e32 v69, v41, v241
	ds_write_b32 v2, v69 offset:9472
	v_mul_f32_e32 v68, v42, v241
	ds_write_b32 v2, v68 offset:9728
	v_mul_f32_e32 v69, v43, v241
	ds_write_b32 v2, v69 offset:9984
	v_mul_f32_e32 v68, v44, v241
	ds_write_b32 v2, v68 offset:10240
	v_mul_f32_e32 v69, v45, v241
	ds_write_b32 v2, v69 offset:10496
	v_mul_f32_e32 v68, v46, v241
	ds_write_b32 v2, v68 offset:10752
	v_mul_f32_e32 v69, v47, v241
	ds_write_b32 v2, v69 offset:11008
	v_mul_f32_e32 v68, v48, v241
	ds_write_b32 v2, v68 offset:11264
	v_mul_f32_e32 v69, v49, v241
	ds_write_b32 v2, v69 offset:11520
	v_mul_f32_e32 v68, v50, v241
	ds_write_b32 v2, v68 offset:11776
	v_mul_f32_e32 v69, v51, v241
	ds_write_b32 v2, v69 offset:12032
	v_mul_f32_e32 v68, v52, v241
	ds_write_b32 v2, v68 offset:12288
	v_mul_f32_e32 v69, v53, v241
	ds_write_b32 v2, v69 offset:12544
	v_mul_f32_e32 v68, v54, v241
	ds_write_b32 v2, v68 offset:12800
	v_mul_f32_e32 v69, v55, v241
	ds_write_b32 v2, v69 offset:13056
	v_mul_f32_e32 v68, v56, v241
	ds_write_b32 v2, v68 offset:13312
	v_mul_f32_e32 v69, v57, v241
	ds_write_b32 v2, v69 offset:13568
	v_mul_f32_e32 v68, v58, v241
	ds_write_b32 v2, v68 offset:13824
	v_mul_f32_e32 v69, v59, v241
	ds_write_b32 v2, v69 offset:14080
	v_mul_f32_e32 v68, v60, v241
	ds_write_b32 v2, v68 offset:14336
	v_mul_f32_e32 v69, v61, v241
	ds_write_b32 v2, v69 offset:14592
	v_mul_f32_e32 v68, v62, v241
	ds_write_b32 v2, v68 offset:14848
	v_mul_f32_e32 v69, v63, v241
	ds_write_b32 v2, v69 offset:15104
	v_mul_f32_e32 v68, v64, v241
	ds_write_b32 v2, v68 offset:15360
	v_mul_f32_e32 v69, v65, v241
	ds_write_b32 v2, v69 offset:15616
	v_mul_f32_e32 v68, v66, v241
	ds_write_b32 v2, v68 offset:15872
	v_mul_f32_e32 v69, v67, v241
	ds_write_b32 v2, v69 offset:16128
	s_waitcnt lgkmcnt(0)
	s_barrier
	s_branch .LaA_epiend_15
; __device__ __forceinline__ void attnA_unit(const P2Ctx& C, int b, int h, int qb) {
;     ...
;     if (comp == 1) {
; #pragma unroll
;         for (int cb = 0; cb < 4; ++cb)
; #pragma unroll
;             for (int r = 0; r < 16; ++r) X2[((qs * 4 + cb) * 16 + r) * 64 + lane] = o[cb][r] * inv;
;     }
;     __syncthreads();
;     if (comp == 0) {
; #pragma unroll
;         for (int cb = 0; cb < 4; ++cb)
; #pragma unroll
;             for (int r = 0; r < 16; ++r) o[cb][r] = o[cb][r] * inv - lam * X2[((qs * 4 + cb) * 16 + r) * 64 + lane];
;         subln_store(o, C.a->in[I_SUBG], C.AO + qrow * DM + h * 128, lane);
	s_nop 0
	s_nop 0
	s_nop 0
	s_nop 0
	s_nop 0
	s_nop 0
	s_nop 0
	s_nop 0
	s_nop 0
	s_nop 0
	s_nop 0
	s_nop 0
	s_nop 0
	s_nop 0
	s_nop 0
	s_nop 0
	s_nop 0
	s_nop 0
	s_nop 0
	s_nop 0
	s_nop 0
	s_nop 0
	s_nop 0
	s_nop 0
	s_nop 0
	s_nop 0
	s_nop 0
	s_nop 0
	s_nop 0
	s_nop 0
	s_nop 0
	s_nop 0
	s_nop 0
	s_nop 0
	s_nop 0
	s_nop 0
	s_nop 0
	s_nop 0
	s_nop 0
	s_nop 0
	s_nop 0
	s_nop 0
	s_nop 0
	s_nop 0
	s_nop 0
	s_nop 0
	s_nop 0
	s_nop 0
	s_nop 0
	s_nop 0
	s_nop 0
	s_nop 0
	s_nop 0
	s_nop 0
	s_nop 0
	s_nop 0
	s_nop 0
	s_nop 0
	s_nop 0
	s_nop 0
	s_nop 0
	s_nop 0
	s_nop 0
	s_nop 0
	s_nop 0
	s_nop 0
	s_nop 0
	s_nop 0
	s_nop 0
	s_nop 0
	s_nop 0
	s_nop 0
	s_nop 0
	s_nop 0
	s_nop 0
	s_nop 0
	s_nop 0
	s_nop 0
	s_nop 0
	s_nop 0
	s_nop 0
	s_nop 0
	s_nop 0
	s_nop 0
	s_nop 0
	s_nop 0
	s_nop 0
	s_nop 0
	s_nop 0
	s_nop 0
	s_nop 0
	s_nop 0
	s_nop 0
	s_nop 0
	s_nop 0
	s_nop 0
	s_nop 0
	s_nop 0
	s_nop 0
	s_nop 0
	s_nop 0
	s_nop 0
	s_nop 0
	s_nop 0
	s_nop 0
	s_nop 0
	s_nop 0
	s_nop 0
	s_nop 0
	s_nop 0
	s_nop 0
	s_nop 0
	s_nop 0
	s_nop 0
	s_nop 0
	s_nop 0
	s_nop 0
	s_nop 0
	s_nop 0
	s_nop 0
	s_nop 0
	s_nop 0
	s_nop 0
	s_nop 0
	s_nop 0
	s_nop 0
	s_nop 0
	s_nop 0
	s_nop 0
	s_nop 0
	s_nop 0
	s_nop 0
	s_nop 0
	s_nop 0
	s_nop 0
	s_nop 0
	s_nop 0
	s_nop 0
	s_nop 0
	s_nop 0
	s_nop 0
	s_nop 0
	s_nop 0
	s_nop 0
	s_nop 0
	s_nop 0
	s_nop 0
	s_nop 0
	s_nop 0
	s_nop 0
	s_nop 0
	s_nop 0
	s_nop 0
	s_nop 0
	s_nop 0
	s_nop 0
	s_nop 0
	s_nop 0
	s_nop 0
	s_nop 0
	s_nop 0
	s_nop 0
	s_nop 0
	s_nop 0
	s_nop 0
	s_nop 0
	s_nop 0
	s_nop 0
	s_nop 0
	s_nop 0
	s_nop 0
	s_nop 0
	s_nop 0
	s_nop 0
	s_nop 0
	s_nop 0
	s_nop 0
	s_nop 0
	s_nop 0
	s_nop 0
	s_nop 0
	s_nop 0
	s_nop 0
	s_nop 0
	s_nop 0
	s_nop 0
	s_nop 0
	s_nop 0
	s_nop 0
	s_nop 0
	s_nop 0
	s_nop 0
	s_nop 0
	s_nop 0
	s_nop 0
	s_nop 0
	s_nop 0
	s_nop 0
	s_nop 0
	s_nop 0
	s_nop 0
	s_nop 0
	s_nop 0
	s_nop 0
	s_nop 0
	s_nop 0
	s_nop 0
	s_nop 0
	s_nop 0
	s_nop 0
	s_nop 0
	s_nop 0
	s_nop 0
	s_nop 0
	s_nop 0
	s_nop 0
	s_nop 0
	s_nop 0
	s_nop 0
	s_nop 0
	s_nop 0
	s_nop 0
	s_nop 0
	s_nop 0
	s_nop 0
	s_nop 0
	s_nop 0
	s_nop 0
	s_nop 0
	s_nop 0
	s_nop 0
	s_nop 0
	s_nop 0
	s_nop 0
	s_nop 0
	s_nop 0
	s_nop 0
	s_nop 0
	s_nop 0
	s_nop 0
	s_nop 0
	s_nop 0
	s_nop 0
	s_nop 0
	s_nop 0
	s_nop 0
	s_nop 0
	s_nop 0
	s_nop 0
	s_nop 0
	s_nop 0
	s_nop 0
	s_nop 0
	s_nop 0
	s_nop 0
	s_nop 0
	s_nop 0
	s_nop 0
	s_nop 0
	s_nop 0
	s_nop 0
	s_nop 0
	s_nop 0
	s_nop 0
	s_nop 0
	s_nop 0
	s_nop 0
	s_nop 0
	s_nop 0
	s_nop 0
	s_nop 0
	s_nop 0
	s_nop 0
	s_nop 0
	s_nop 0
	s_nop 0
	s_nop 0
	s_nop 0
	s_nop 0
	s_nop 0
	s_nop 0
	s_nop 0
	s_nop 0
	s_nop 0
	s_nop 0
	s_nop 0
	s_nop 0
	s_nop 0
	s_nop 0
	s_nop 0
	s_nop 0
	s_nop 0
	s_nop 0
	s_nop 0
	s_nop 0
	s_nop 0
	s_nop 0
	s_nop 0
	s_nop 0
	s_nop 0
	s_nop 0
	s_nop 0
	s_nop 0
	s_nop 0
	s_nop 0
	s_nop 0
	s_nop 0
	s_nop 0
	s_nop 0
	s_nop 0
	s_nop 0
	s_nop 0
	s_nop 0
	s_nop 0
	s_nop 0
	s_nop 0
	s_nop 0
	s_nop 0
	s_nop 0
	s_nop 0
	s_nop 0
	s_nop 0
	s_nop 0
	s_nop 0
	s_nop 0
	s_nop 0
	s_nop 0
	s_nop 0
	s_nop 0
	s_nop 0
	s_nop 0
	s_nop 0
	s_nop 0
	s_nop 0
	s_nop 0
	s_nop 0
	s_nop 0
	s_nop 0
	s_nop 0
	s_nop 0
	s_nop 0
	s_nop 0
	s_nop 0
	s_nop 0
	s_nop 0
	s_nop 0
	s_nop 0
	s_nop 0
	s_nop 0
	s_nop 0
	s_nop 0
	s_nop 0
	s_nop 0
	s_nop 0
	s_nop 0
	s_nop 0
	s_nop 0
	s_nop 0
	s_nop 0
	s_nop 0
	s_nop 0
	s_nop 0
	s_nop 0
	s_nop 0
	s_nop 0
	s_nop 0
	s_nop 0
	s_nop 0
	s_nop 0
	s_nop 0
	s_nop 0
	s_nop 0
	s_nop 0
	s_nop 0
	s_nop 0
	s_nop 0
	s_nop 0
	s_nop 0
	s_nop 0
	s_nop 0
	s_nop 0
	s_nop 0
	s_nop 0
	s_nop 0
	s_nop 0
	s_nop 0
	s_nop 0
	s_nop 0
	s_nop 0
	s_nop 0
	s_nop 0
	s_nop 0
	s_nop 0
	s_nop 0
	s_nop 0
	s_nop 0
	s_nop 0
	s_nop 0
	s_nop 0
	s_nop 0
	s_nop 0
	s_nop 0
	s_nop 0
	s_nop 0
	s_nop 0
	s_nop 0
	s_nop 0
	s_nop 0
	s_nop 0
	s_nop 0
	s_nop 0
	s_nop 0
	s_nop 0
	s_nop 0
	s_nop 0
	s_nop 0
	s_nop 0
	s_nop 0
	s_nop 0
	s_nop 0
	s_nop 0
	s_nop 0
	s_nop 0
	s_nop 0
	s_nop 0
	s_nop 0
	s_nop 0
	s_nop 0
	s_nop 0
	s_nop 0
	s_nop 0
	s_nop 0
	s_nop 0
	s_nop 0
	s_nop 0
	s_nop 0
	s_nop 0
	s_nop 0
	s_nop 0
	s_nop 0
	s_nop 0
	s_nop 0
	s_nop 0
	s_nop 0
	s_nop 0
	s_nop 0
	s_nop 0
	s_nop 0
	s_nop 0
	s_nop 0
	s_nop 0
	s_nop 0
	s_nop 0
	s_nop 0
	s_nop 0
	s_nop 0
	s_nop 0
	s_nop 0
	s_nop 0
	s_nop 0
	s_nop 0
	s_nop 0
	s_nop 0
	s_nop 0
	s_nop 0
	s_nop 0
	s_nop 0
	s_nop 0
	s_nop 0
	s_nop 0
	s_nop 0
	s_nop 0
	s_nop 0
	s_nop 0
	s_nop 0
	s_nop 0
	s_nop 0
	s_nop 0
	s_nop 0
	s_nop 0
	s_nop 0
	s_nop 0
	s_nop 0
	s_nop 0
	s_nop 0
	s_nop 0
	s_nop 0
	s_nop 0
	s_nop 0
	s_nop 0
	s_nop 0
	s_nop 0
	s_nop 0
	s_nop 0
	s_nop 0
	s_nop 0
	s_nop 0
	s_nop 0
	s_nop 0
	s_nop 0
	s_nop 0
	s_nop 0
	s_nop 0
	s_nop 0
	s_nop 0
	s_nop 0
	s_nop 0
	s_nop 0
	s_nop 0
	s_nop 0
	s_nop 0
	s_nop 0
	s_nop 0
	s_nop 0
	s_nop 0
	s_nop 0
	s_nop 0
	s_nop 0
	s_nop 0
	s_nop 0
	s_nop 0
	s_nop 0
	s_nop 0
	s_nop 0
	s_nop 0
	s_nop 0
	s_nop 0
	s_nop 0
	s_nop 0
	s_nop 0
	s_nop 0
	s_nop 0
	s_nop 0
	s_nop 0
	s_nop 0
	s_nop 0
	s_nop 0
	s_nop 0
	s_nop 0
	s_nop 0
	s_nop 0
	s_nop 0
	s_nop 0
	s_nop 0
	s_nop 0
	s_nop 0
	s_nop 0
	s_nop 0
	s_nop 0
	s_nop 0
	s_nop 0
	s_nop 0
	s_nop 0
	s_nop 0
	s_nop 0
	s_nop 0
	s_nop 0
	s_nop 0
	s_nop 0
	s_nop 0
	s_nop 0
	s_nop 0
	s_nop 0
	s_nop 0
	s_nop 0
	s_nop 0
	s_nop 0
	s_nop 0
	s_nop 0
	s_nop 0
	s_nop 0
	s_nop 0
	s_nop 0
	s_nop 0
	s_nop 0
	s_nop 0
	s_nop 0
	s_nop 0
	s_nop 0
	s_nop 0
	s_nop 0
	s_nop 0
	s_nop 0
	s_nop 0
	s_nop 0
	s_nop 0
	s_nop 0
	s_nop 0
	s_nop 0
	s_nop 0
	s_nop 0
	s_nop 0
	s_nop 0
	s_nop 0
	s_nop 0
	s_nop 0
	s_nop 0
	s_nop 0
	s_nop 0
	s_nop 0
	s_nop 0
	s_nop 0
	s_nop 0
	s_nop 0
	s_nop 0
	s_nop 0
	s_nop 0
	s_nop 0
	s_nop 0
	s_nop 0
	s_nop 0
	s_nop 0
	s_nop 0
	s_nop 0
	s_nop 0
	s_nop 0
	s_nop 0
	s_nop 0
	s_nop 0
	s_nop 0
	s_nop 0
	s_nop 0
	s_nop 0
	s_nop 0
	s_nop 0
	s_nop 0
	s_nop 0
	s_nop 0
	s_nop 0
	s_nop 0
	s_nop 0
	s_nop 0
	s_nop 0
	s_nop 0
	s_nop 0
	s_nop 0
	s_nop 0
	s_nop 0
	s_nop 0
	s_nop 0
	s_nop 0
	s_nop 0
	s_nop 0
	s_nop 0
	s_nop 0
	s_nop 0
	s_nop 0
	s_nop 0
	s_nop 0
	s_nop 0
	s_nop 0
	s_nop 0
	s_nop 0
	s_nop 0
	s_nop 0
	s_nop 0
	s_nop 0
	s_nop 0
	s_nop 0
	s_nop 0
	s_nop 0
	s_nop 0
	s_nop 0
	s_nop 0
	s_nop 0
	s_nop 0
	s_nop 0
	s_nop 0
	s_nop 0
	s_nop 0
	s_nop 0
	s_nop 0
	s_nop 0
	s_nop 0
	s_nop 0
	s_nop 0
	s_nop 0
	s_nop 0
	s_nop 0
	s_nop 0
	s_nop 0
	s_nop 0
	s_nop 0
	s_nop 0
	s_nop 0
	s_nop 0
	s_nop 0
	s_nop 0
	s_nop 0
	s_nop 0
	s_nop 0
	s_nop 0
	s_nop 0
	s_nop 0
	s_nop 0
	s_nop 0
	s_nop 0
	s_nop 0
	s_nop 0
	s_nop 0
	s_nop 0
	s_nop 0
	s_nop 0
	s_nop 0
	s_nop 0
	s_nop 0
	s_nop 0
	s_nop 0
	s_nop 0
	s_nop 0
	s_nop 0
	s_nop 0
	s_nop 0
	s_nop 0
	s_nop 0
	s_nop 0
	s_nop 0
	s_nop 0
	s_nop 0
	s_nop 0
	s_nop 0
	s_nop 0
	s_nop 0
	s_nop 0
	s_nop 0
	s_nop 0
	s_nop 0
	s_nop 0
	s_nop 0
	s_nop 0
	s_nop 0
	s_nop 0
	s_nop 0
	s_nop 0
	s_nop 0
	s_nop 0
	s_nop 0
	s_nop 0
	s_nop 0
	s_nop 0
	s_nop 0
	s_nop 0
	s_nop 0
